# T15 static-V loop + s_setprio 2 for the MFMA/VALU stream, 0 during the LDS-read/global-load/LDS-write prefix of each stage
# speedup vs baseline: 1.0199x; 1.0007x over previous
; #define MFMA32(a, b, c) __builtin_amdgcn_mfma_f32_32x32x16_bf16((a), (b), (c), 0, 0, 0)
; template <int DQK, bool SB, bool SMAX>
; DI void attn_item(const Params& p, char* smem, int bh, int qb, float Mb) {
;     ...
;   const int blk = (lane >> 4) & 1, tq = (lane & 15) >> 2, tp = lane & 3;
;   const int voff = (4 * h + tq) * VSTR + 16 * blk + 4 * tp;
;   AT_LOAD(0, 0)
;   AT_WRITE(0, 0)
;   AT_LOAD(0, 1)
;   __syncthreads();
;   bool stop = false;
;   for (int it2 = 0; it2 < nt && !stop; it2 += 2) {
; #pragma unroll
;    for (int st2 = 0; st2 < 2; ++st2) {
;     const int it = it2 + st2;
;     const int kb0 = AT_KB(it);
;     const bf16_t* kc = Ks + st2 * KBUF;
;     const bf16_t* vc = Vs + st2 * VBUF;
;     const bool active = kb0 < qw0 + 32;
;     f32x16 st[2];
;     if (active) {
; #pragma unroll
;       for (int kb = 0; kb < 2; ++kb)
; #pragma unroll
;         for (int i = 0; i < 16; ++i) st[kb][i] = SMAX ? negM[i] : 0.f;
; #pragma unroll
;       for (int ks = 0; ks < NKS; ++ks)
; #pragma unroll
;         for (int kb = 0; kb < 2; ++kb) {
;           const bf16x8 a = *(const bf16x8*)(kc + (kb * 32 + r) * KSTR + ks * 16 + h * 8);
;           st[kb] = MFMA32(a, qf[ks], st[kb]);
;         }
;     }
;     __builtin_amdgcn_sched_barrier(0);
;     AT_WRITE(0, st2 ^ 1)
;     AT_LOAD(0, (it + 2 < nt) ? it + 2 : nt - 1)
;     if (active) {
;       const bool diag = (kb0 + 64 > qw0);
;       bf16x8 pk[4];
;     ...
; #pragma unroll
;       for (int kb = 0; kb < 2; ++kb)
; #pragma unroll
;         for (int s = 0; s < 2; ++s) {
;           u32x4 w;
; #pragma unroll
;           for (int e = 0; e < 4; ++e) w[e] = pk_bf16(st[kb][8 * s + 2 * e], st[kb][8 * s + 2 * e + 1]);
;           pk[kb * 2 + s] = __builtin_bit_cast(bf16x8, w);
;         }
; #pragma unroll
;       for (int kk = 0; kk < 4; ++kk)
; #pragma unroll
;         for (int db = 0; db < 2; ++db) {
;           const s16x4 v0 = __builtin_amdgcn_ds_read_tr16_b64_v4i16((lds_s16x4*)(vc + voff + (16 * kk) * VSTR + 32 * db));
;           const s16x4 v1 = __builtin_amdgcn_ds_read_tr16_b64_v4i16((lds_s16x4*)(vc + voff + (16 * kk + 8) * VSTR + 32 * db));
;           const bf16x8 vf = __builtin_shufflevector(v0, v1, 0, 1, 2, 3, 4, 5, 6, 7);
;           O[db] = MFMA32(vf, pk[kk], O[db]);
;         }
.Lt15_loop:
	s_setprio 0
	ds_read_b128 v[216:219], v153 offset:13312
	ds_read_b128 v[220:223], v153 offset:19968
	ds_read_b128 v[228:231], v153 offset:13344
	ds_read_b64_tr_b16 v[236:237], v154 offset:26624
	ds_read_b64_tr_b16 v[238:239], v154 offset:27776
	ds_read_b64_tr_b16 v[244:245], v154 offset:26688
	ds_read_b64_tr_b16 v[246:247], v154 offset:27840
	ds_read_b64_tr_b16 v[248:249], v154 offset:28928
	ds_read_b64_tr_b16 v[250:251], v154 offset:30080
	s_min_i32 s2, s14, s4
	s_mul_i32 s3, s2, 0x3000
	s_add_u32 s30, s22, s3
	s_addc_u32 s31, s23, 0
	s_add_u32 s34, s30, 0x1000
	s_addc_u32 s35, s31, 0
	s_add_i32 s3, s14, -1
	s_min_i32 s3, s3, s4
	s_lshl_b32 s3, s3, 13
	s_add_u32 s36, s38, s3
	s_addc_u32 s37, s39, 0
	global_load_dwordx4 v[132:135], v174, s[30:31] offset:-4096
	global_load_dwordx4 v[136:139], v174, s[30:31]
	global_load_dwordx4 v[140:143], v174, s[34:35]
	global_load_dwordx4 v[144:147], v174, s[36:37] offset:-4096
	global_load_dwordx4 v[148:151], v174, s[36:37]
	s_waitcnt vmcnt(9)
	ds_write_b128 v206, v[112:115]
	s_waitcnt vmcnt(8)
	ds_write_b128 v207, v[116:119]
	s_waitcnt vmcnt(7)
	ds_write_b128 v208, v[120:123]
	s_waitcnt vmcnt(6)
	ds_write_b128 v203, v[124:127] offset:35840
	s_waitcnt vmcnt(5)
	ds_write_b128 v203, v[128:131] offset:40448
	s_setprio 2
	v_exp_f32_e32 v48, v48
	v_exp_f32_e32 v49, v49
	v_exp_f32_e32 v50, v50
	v_exp_f32_e32 v51, v51
	s_waitcnt lgkmcnt(13)
	v_mfma_f32_32x32x16_bf16 v[0:15], v[216:219], v[80:83], 0
	ds_read_b128 v[216:219], v153 offset:20000
	v_exp_f32_e32 v52, v52
	v_add_f32_e32 v224, v49, v48
	v_cvt_pk_bf16_f32 v188, v48, v49
	v_exp_f32_e32 v53, v53
	s_waitcnt lgkmcnt(13)
	v_mfma_f32_32x32x16_bf16 v[156:171], v[220:223], v[80:83], 0
	ds_read_b128 v[220:223], v153 offset:13376
	v_add_f32_e32 v224, v50, v224
	v_exp_f32_e32 v54, v54
	v_add_f32_e32 v224, v51, v224
	v_cvt_pk_bf16_f32 v189, v50, v51
	s_waitcnt lgkmcnt(13)
	v_mfma_f32_32x32x16_bf16 v[0:15], v[228:231], v[84:87], v[0:15]
	ds_read_b128 v[228:231], v153 offset:20032
	v_exp_f32_e32 v55, v55
	v_add_f32_e32 v224, v52, v224
	v_exp_f32_e32 v56, v56
	v_add_f32_e32 v224, v53, v224
	s_waitcnt lgkmcnt(2)
	v_mfma_f32_32x32x16_bf16 v[156:171], v[216:219], v[84:87], v[156:171]
	ds_read_b128 v[216:219], v153 offset:13408
	v_cvt_pk_bf16_f32 v190, v52, v53
	v_exp_f32_e32 v57, v57
	v_add_f32_e32 v224, v54, v224
	v_exp_f32_e32 v58, v58
	s_waitcnt lgkmcnt(2)
	v_mfma_f32_32x32x16_bf16 v[0:15], v[220:223], v[88:91], v[0:15]
	ds_read_b128 v[220:223], v153 offset:20064
	v_add_f32_e32 v224, v55, v224
	v_cvt_pk_bf16_f32 v191, v54, v55
	v_exp_f32_e32 v59, v59
	v_add_f32_e32 v224, v56, v224
	s_nop 0
	v_mfma_f32_32x32x16_bf16 v[32:47], v[236:239], v[188:191], v[32:47]
	ds_read_b64_tr_b16 v[236:237], v154 offset:28992
	ds_read_b64_tr_b16 v[238:239], v154 offset:30144
	v_exp_f32_e32 v60, v60
	v_add_f32_e32 v224, v57, v224
	v_cvt_pk_bf16_f32 v192, v56, v57
	v_exp_f32_e32 v61, v61
	v_mfma_f32_32x32x16_bf16 v[16:31], v[244:247], v[188:191], v[16:31]
	ds_read_b64_tr_b16 v[244:245], v154 offset:31232
	ds_read_b64_tr_b16 v[246:247], v154 offset:32384
	v_add_f32_e32 v224, v58, v224
	v_exp_f32_e32 v62, v62
	v_add_f32_e32 v224, v59, v224
	v_cvt_pk_bf16_f32 v193, v58, v59
	s_waitcnt lgkmcnt(6)
	v_mfma_f32_32x32x16_bf16 v[156:171], v[228:231], v[88:91], v[156:171]
	ds_read_b128 v[228:231], v153 offset:13440
	v_exp_f32_e32 v63, v63
	v_add_f32_e32 v224, v60, v224
	v_add_f32_e32 v224, v61, v224
	v_add_f32_e32 v224, v62, v224
	s_waitcnt lgkmcnt(6)
	v_mfma_f32_32x32x16_bf16 v[0:15], v[216:219], v[92:95], v[0:15]
	ds_read_b128 v[216:219], v153 offset:20096
	v_add_f32_e32 v224, v63, v224
	v_cvt_pk_bf16_f32 v194, v60, v61
	v_cvt_pk_bf16_f32 v195, v62, v63
	v_exp_f32_e32 v64, v64
	s_waitcnt lgkmcnt(6)
	v_mfma_f32_32x32x16_bf16 v[156:171], v[220:223], v[92:95], v[156:171]
	ds_read_b128 v[220:223], v153 offset:13472
	v_exp_f32_e32 v65, v65
	v_exp_f32_e32 v66, v66
	v_exp_f32_e32 v67, v67
	v_add_f32_e32 v224, v64, v224
	v_mfma_f32_32x32x16_bf16 v[32:47], v[248:251], v[192:195], v[32:47]
	ds_read_b64_tr_b16 v[248:249], v154 offset:31296
	ds_read_b64_tr_b16 v[250:251], v154 offset:32448
	v_exp_f32_e32 v68, v68
	v_add_f32_e32 v224, v65, v224
	v_cvt_pk_bf16_f32 v188, v64, v65
	v_exp_f32_e32 v69, v69
	s_waitcnt lgkmcnt(7)
	v_mfma_f32_32x32x16_bf16 v[16:31], v[236:239], v[192:195], v[16:31]
	ds_read_b64_tr_b16 v[236:237], v154 offset:33536
	ds_read_b64_tr_b16 v[238:239], v154 offset:34688
	v_add_f32_e32 v224, v66, v224
	v_exp_f32_e32 v70, v70
	v_add_f32_e32 v224, v67, v224
	v_cvt_pk_bf16_f32 v189, v66, v67
	s_waitcnt lgkmcnt(6)
	v_mfma_f32_32x32x16_bf16 v[0:15], v[228:231], v[104:107], v[0:15]
	ds_read_b128 v[228:231], v153 offset:20128
	v_exp_f32_e32 v71, v71
	v_add_f32_e32 v224, v68, v224
	v_exp_f32_e32 v72, v72
	v_add_f32_e32 v224, v69, v224
	s_waitcnt lgkmcnt(6)
	v_mfma_f32_32x32x16_bf16 v[156:171], v[216:219], v[104:107], v[156:171]
	v_cvt_pk_bf16_f32 v190, v68, v69
	v_exp_f32_e32 v73, v73
	v_add_f32_e32 v224, v70, v224
	v_exp_f32_e32 v74, v74
	s_waitcnt lgkmcnt(5)
	v_mfma_f32_32x32x16_bf16 v[0:15], v[220:223], v[108:111], v[0:15]
	v_add_f32_e32 v224, v71, v224
	v_cvt_pk_bf16_f32 v191, v70, v71
	v_exp_f32_e32 v75, v75
	v_add_f32_e32 v224, v72, v224
	s_nop 0
	v_mfma_f32_32x32x16_bf16 v[32:47], v[244:247], v[188:191], v[32:47]
	ds_read_b64_tr_b16 v[244:245], v154 offset:33600
	ds_read_b64_tr_b16 v[246:247], v154 offset:34752
	v_exp_f32_e32 v76, v76
	v_add_f32_e32 v224, v73, v224
	v_cvt_pk_bf16_f32 v192, v72, v73
	v_exp_f32_e32 v77, v77
	s_waitcnt lgkmcnt(5)
	v_mfma_f32_32x32x16_bf16 v[16:31], v[248:251], v[188:191], v[16:31]
	v_add_f32_e32 v224, v74, v224
	v_exp_f32_e32 v78, v78
	v_add_f32_e32 v224, v75, v224
	v_cvt_pk_bf16_f32 v193, v74, v75
	s_waitcnt lgkmcnt(2)
	v_mfma_f32_32x32x16_bf16 v[156:171], v[228:231], v[108:111], v[156:171]
	v_exp_f32_e32 v79, v79
	v_add_f32_e32 v224, v76, v224
	v_add_f32_e32 v224, v77, v224
	v_add_f32_e32 v224, v78, v224
	v_add_f32_e32 v224, v79, v224
	v_cvt_pk_bf16_f32 v194, v76, v77
	v_cvt_pk_bf16_f32 v195, v78, v79
	s_nop 1
	v_mfma_f32_32x32x16_bf16 v[32:47], v[236:239], v[192:195], v[32:47]
	s_waitcnt lgkmcnt(0)
	v_mfma_f32_32x32x16_bf16 v[16:31], v[244:247], v[192:195], v[16:31]
	v_add_f32_e32 v152, v152, v224
	s_waitcnt lgkmcnt(0)
	s_barrier
; #define MFMA32(a, b, c) __builtin_amdgcn_mfma_f32_32x32x16_bf16((a), (b), (c), 0, 0, 0)
; template <int DQK, bool SB, bool SMAX>
; DI void attn_item(const Params& p, char* smem, int bh, int qb, float Mb) {
;     ...
;   const int blk = (lane >> 4) & 1, tq = (lane & 15) >> 2, tp = lane & 3;
;   const int voff = (4 * h + tq) * VSTR + 16 * blk + 4 * tp;
;   AT_LOAD(0, 0)
;   AT_WRITE(0, 0)
;   AT_LOAD(0, 1)
;   __syncthreads();
;   bool stop = false;
;   for (int it2 = 0; it2 < nt && !stop; it2 += 2) {
; #pragma unroll
;    for (int st2 = 0; st2 < 2; ++st2) {
;     const int it = it2 + st2;
;     const int kb0 = AT_KB(it);
;     const bf16_t* kc = Ks + st2 * KBUF;
;     const bf16_t* vc = Vs + st2 * VBUF;
;     const bool active = kb0 < qw0 + 32;
;     f32x16 st[2];
;     if (active) {
; #pragma unroll
;       for (int kb = 0; kb < 2; ++kb)
; #pragma unroll
;         for (int i = 0; i < 16; ++i) st[kb][i] = SMAX ? negM[i] : 0.f;
; #pragma unroll
;       for (int ks = 0; ks < NKS; ++ks)
; #pragma unroll
;         for (int kb = 0; kb < 2; ++kb) {
;           const bf16x8 a = *(const bf16x8*)(kc + (kb * 32 + r) * KSTR + ks * 16 + h * 8);
;           st[kb] = MFMA32(a, qf[ks], st[kb]);
;         }
;     }
;     __builtin_amdgcn_sched_barrier(0);
;     AT_WRITE(0, st2 ^ 1)
;     AT_LOAD(0, (it + 2 < nt) ? it + 2 : nt - 1)
;     if (active) {
;       const bool diag = (kb0 + 64 > qw0);
;       bf16x8 pk[4];
;     ...
; #pragma unroll
;       for (int kb = 0; kb < 2; ++kb)
; #pragma unroll
;         for (int s = 0; s < 2; ++s) {
;           u32x4 w;
; #pragma unroll
;           for (int e = 0; e < 4; ++e) w[e] = pk_bf16(st[kb][8 * s + 2 * e], st[kb][8 * s + 2 * e + 1]);
;           pk[kb * 2 + s] = __builtin_bit_cast(bf16x8, w);
;         }
; #pragma unroll
;       for (int kk = 0; kk < 4; ++kk)
; #pragma unroll
;         for (int db = 0; db < 2; ++db) {
;           const s16x4 v0 = __builtin_amdgcn_ds_read_tr16_b64_v4i16((lds_s16x4*)(vc + voff + (16 * kk) * VSTR + 32 * db));
;           const s16x4 v1 = __builtin_amdgcn_ds_read_tr16_b64_v4i16((lds_s16x4*)(vc + voff + (16 * kk + 8) * VSTR + 32 * db));
;           const bf16x8 vf = __builtin_shufflevector(v0, v1, 0, 1, 2, 3, 4, 5, 6, 7);
;           O[db] = MFMA32(vf, pk[kk], O[db]);
;         }
	s_add_i32 s14, s14, 1
	s_setprio 0
	ds_read_b128 v[216:219], v153
	ds_read_b128 v[220:223], v153 offset:6656
	ds_read_b128 v[228:231], v153 offset:32
	ds_read_b64_tr_b16 v[236:237], v154 offset:35840
	ds_read_b64_tr_b16 v[238:239], v154 offset:36992
	ds_read_b64_tr_b16 v[244:245], v154 offset:35904
	ds_read_b64_tr_b16 v[246:247], v154 offset:37056
	ds_read_b64_tr_b16 v[248:249], v154 offset:38144
	ds_read_b64_tr_b16 v[250:251], v154 offset:39296
	s_min_i32 s2, s14, s4
	s_mul_i32 s3, s2, 0x3000
	s_add_u32 s30, s22, s3
	s_addc_u32 s31, s23, 0
	s_add_u32 s34, s30, 0x1000
	s_addc_u32 s35, s31, 0
	s_add_i32 s3, s14, -1
	s_min_i32 s3, s3, s4
	s_lshl_b32 s3, s3, 13
	s_add_u32 s36, s38, s3
	s_addc_u32 s37, s39, 0
	global_load_dwordx4 v[112:115], v174, s[30:31] offset:-4096
	global_load_dwordx4 v[116:119], v174, s[30:31]
	global_load_dwordx4 v[120:123], v174, s[34:35]
	global_load_dwordx4 v[124:127], v174, s[36:37] offset:-4096
	global_load_dwordx4 v[128:131], v174, s[36:37]
	s_waitcnt vmcnt(9)
	ds_write_b128 v206, v[132:135] offset:13312
	s_waitcnt vmcnt(8)
	ds_write_b128 v207, v[136:139] offset:13312
	s_waitcnt vmcnt(7)
	ds_write_b128 v208, v[140:143] offset:13312
	s_waitcnt vmcnt(6)
	ds_write_b128 v203, v[144:147] offset:26624
	s_waitcnt vmcnt(5)
	ds_write_b128 v203, v[148:151] offset:31232
	s_setprio 2
	v_exp_f32_e32 v0, v0
	v_exp_f32_e32 v1, v1
	v_exp_f32_e32 v2, v2
	v_exp_f32_e32 v3, v3
	s_waitcnt lgkmcnt(13)
	v_mfma_f32_32x32x16_bf16 v[48:63], v[216:219], v[80:83], 0
	ds_read_b128 v[216:219], v153 offset:6688
	v_exp_f32_e32 v4, v4
	v_add_f32_e32 v224, v1, v0
	v_cvt_pk_bf16_f32 v188, v0, v1
	v_exp_f32_e32 v5, v5
	s_waitcnt lgkmcnt(13)
	v_mfma_f32_32x32x16_bf16 v[64:79], v[220:223], v[80:83], 0
	ds_read_b128 v[220:223], v153 offset:64
	v_add_f32_e32 v224, v2, v224
	v_exp_f32_e32 v6, v6
	v_add_f32_e32 v224, v3, v224
	v_cvt_pk_bf16_f32 v189, v2, v3
	s_waitcnt lgkmcnt(13)
	v_mfma_f32_32x32x16_bf16 v[48:63], v[228:231], v[84:87], v[48:63]
	ds_read_b128 v[228:231], v153 offset:6720
	v_exp_f32_e32 v7, v7
	v_add_f32_e32 v224, v4, v224
	v_exp_f32_e32 v8, v8
	v_add_f32_e32 v224, v5, v224
	s_waitcnt lgkmcnt(2)
	v_mfma_f32_32x32x16_bf16 v[64:79], v[216:219], v[84:87], v[64:79]
	ds_read_b128 v[216:219], v153 offset:96
	v_cvt_pk_bf16_f32 v190, v4, v5
	v_exp_f32_e32 v9, v9
	v_add_f32_e32 v224, v6, v224
	v_exp_f32_e32 v10, v10
	s_waitcnt lgkmcnt(2)
	v_mfma_f32_32x32x16_bf16 v[48:63], v[220:223], v[88:91], v[48:63]
	ds_read_b128 v[220:223], v153 offset:6752
	v_add_f32_e32 v224, v7, v224
	v_cvt_pk_bf16_f32 v191, v6, v7
	v_exp_f32_e32 v11, v11
	v_add_f32_e32 v224, v8, v224
	s_nop 0
	v_mfma_f32_32x32x16_bf16 v[32:47], v[236:239], v[188:191], v[32:47]
	ds_read_b64_tr_b16 v[236:237], v154 offset:38208
	ds_read_b64_tr_b16 v[238:239], v154 offset:39360
	v_exp_f32_e32 v12, v12
	v_add_f32_e32 v224, v9, v224
	v_cvt_pk_bf16_f32 v192, v8, v9
	v_exp_f32_e32 v13, v13
	v_mfma_f32_32x32x16_bf16 v[16:31], v[244:247], v[188:191], v[16:31]
	ds_read_b64_tr_b16 v[244:245], v154 offset:40448
	ds_read_b64_tr_b16 v[246:247], v154 offset:41600
	v_add_f32_e32 v224, v10, v224
	v_exp_f32_e32 v14, v14
	v_add_f32_e32 v224, v11, v224
	v_cvt_pk_bf16_f32 v193, v10, v11
	s_waitcnt lgkmcnt(6)
	v_mfma_f32_32x32x16_bf16 v[64:79], v[228:231], v[88:91], v[64:79]
	ds_read_b128 v[228:231], v153 offset:128
	v_exp_f32_e32 v15, v15
	v_add_f32_e32 v224, v12, v224
	v_add_f32_e32 v224, v13, v224
	v_add_f32_e32 v224, v14, v224
	s_waitcnt lgkmcnt(6)
	v_mfma_f32_32x32x16_bf16 v[48:63], v[216:219], v[92:95], v[48:63]
	ds_read_b128 v[216:219], v153 offset:6784
	v_add_f32_e32 v224, v15, v224
	v_cvt_pk_bf16_f32 v194, v12, v13
	v_cvt_pk_bf16_f32 v195, v14, v15
	v_exp_f32_e32 v156, v156
	s_waitcnt lgkmcnt(6)
	v_mfma_f32_32x32x16_bf16 v[64:79], v[220:223], v[92:95], v[64:79]
	ds_read_b128 v[220:223], v153 offset:160
	v_exp_f32_e32 v157, v157
	v_exp_f32_e32 v158, v158
	v_exp_f32_e32 v159, v159
	v_add_f32_e32 v224, v156, v224
	v_mfma_f32_32x32x16_bf16 v[32:47], v[248:251], v[192:195], v[32:47]
	ds_read_b64_tr_b16 v[248:249], v154 offset:40512
	ds_read_b64_tr_b16 v[250:251], v154 offset:41664
	v_exp_f32_e32 v160, v160
	v_add_f32_e32 v224, v157, v224
	v_cvt_pk_bf16_f32 v188, v156, v157
	v_exp_f32_e32 v161, v161
	s_waitcnt lgkmcnt(7)
	v_mfma_f32_32x32x16_bf16 v[16:31], v[236:239], v[192:195], v[16:31]
	ds_read_b64_tr_b16 v[236:237], v154 offset:42752
	ds_read_b64_tr_b16 v[238:239], v154 offset:43904
	v_add_f32_e32 v224, v158, v224
	v_exp_f32_e32 v162, v162
	v_add_f32_e32 v224, v159, v224
	v_cvt_pk_bf16_f32 v189, v158, v159
	s_waitcnt lgkmcnt(6)
	v_mfma_f32_32x32x16_bf16 v[48:63], v[228:231], v[104:107], v[48:63]
	ds_read_b128 v[228:231], v153 offset:6816
	v_exp_f32_e32 v163, v163
	v_add_f32_e32 v224, v160, v224
	v_exp_f32_e32 v164, v164
	v_add_f32_e32 v224, v161, v224
	s_waitcnt lgkmcnt(6)
	v_mfma_f32_32x32x16_bf16 v[64:79], v[216:219], v[104:107], v[64:79]
	v_cvt_pk_bf16_f32 v190, v160, v161
	v_exp_f32_e32 v165, v165
	v_add_f32_e32 v224, v162, v224
	v_exp_f32_e32 v166, v166
	s_waitcnt lgkmcnt(5)
	v_mfma_f32_32x32x16_bf16 v[48:63], v[220:223], v[108:111], v[48:63]
	v_add_f32_e32 v224, v163, v224
	v_cvt_pk_bf16_f32 v191, v162, v163
	v_exp_f32_e32 v167, v167
	v_add_f32_e32 v224, v164, v224
	s_nop 0
	v_mfma_f32_32x32x16_bf16 v[32:47], v[244:247], v[188:191], v[32:47]
	ds_read_b64_tr_b16 v[244:245], v154 offset:42816
	ds_read_b64_tr_b16 v[246:247], v154 offset:43968
	v_exp_f32_e32 v168, v168
	v_add_f32_e32 v224, v165, v224
	v_cvt_pk_bf16_f32 v192, v164, v165
	v_exp_f32_e32 v169, v169
	s_waitcnt lgkmcnt(5)
	v_mfma_f32_32x32x16_bf16 v[16:31], v[248:251], v[188:191], v[16:31]
	v_add_f32_e32 v224, v166, v224
	v_exp_f32_e32 v170, v170
	v_add_f32_e32 v224, v167, v224
	v_cvt_pk_bf16_f32 v193, v166, v167
	s_waitcnt lgkmcnt(2)
	v_mfma_f32_32x32x16_bf16 v[64:79], v[228:231], v[108:111], v[64:79]
	v_exp_f32_e32 v171, v171
	v_add_f32_e32 v224, v168, v224
	v_add_f32_e32 v224, v169, v224
	v_add_f32_e32 v224, v170, v224
	v_add_f32_e32 v224, v171, v224
	v_cvt_pk_bf16_f32 v194, v168, v169
	v_cvt_pk_bf16_f32 v195, v170, v171
	s_nop 1
	v_mfma_f32_32x32x16_bf16 v[32:47], v[236:239], v[192:195], v[32:47]
	s_waitcnt lgkmcnt(0)
	v_mfma_f32_32x32x16_bf16 v[16:31], v[244:247], v[192:195], v[16:31]
	v_add_f32_e32 v152, v152, v224
	s_waitcnt lgkmcnt(0)
	s_barrier
	s_add_i32 s14, s14, 1
	s_add_i32 s21, s21, -1
	s_cmp_lg_u32 s21, 0
	s_cbranch_scc1 .Lt15_loop
